# baseline (speedup 1.0000x reference)
; #define BAR __builtin_amdgcn_s_barrier()
; template <int EPI, int N, int K>
; __device__ __forceinline__ void gemm_phase(const bf16_t* __restrict__ A, const bf16_t* __restrict__ Bt, const EpiArgs ea) {
;     ...
;       asm volatile("s_waitcnt lgkmcnt(0)" ::: "memory"); BAR;
; #pragma unroll
;       for (int ai = 0; ai < 2; ++ai)
; #pragma unroll
;         for (int m = 0; m < 4; ++m) {
;           const f32x4 r4 = *(const f32x4*)(rstd_l + ai * 128 + wr * 64 + m * 16 + fq * 4);
; #pragma unroll
;           for (int j = 0; j < 4; ++j) {
;             const int row = brow + ai * 128 + wr * 64 + m * 16 + fq * 4 + j;
;             const float rs = r4[j];
;             float v0 = acc[ai][0][m][0][j] * rs, v1 = acc[ai][0][m][1][j] * rs, v2 = acc[ai][1][m][0][j] * rs, v3 = acc[ai][1][m][1][j] * rs;
;             if (EPI == EPI_MLP) {
;               v0 = fmaxf(v0, 0.f); v1 = fmaxf(v1, 0.f); v2 = fmaxf(v2, 0.f); v3 = fmaxf(v3, 0.f);
;               v0 *= v0; v1 *= v1; v2 *= v2; v3 *= v3;
;             }
;             u32x2 o = {pk2(v0, v1), pk2(v2, v3)};
;             st_wt(ea.outb + (size_t)row * N + c0, o);
;           }
;         }
.LBB0_125:
	s_or_b64 exec, exec, s[2:3]
	s_waitcnt lgkmcnt(0)
	s_barrier
	ds_read_b128 v[154:157], v137
	ds_read_b128 v[158:161], v137 offset:64
	ds_read_b128 v[162:165], v137 offset:128
	ds_read_b128 v[166:169], v137 offset:192
	ds_read_b128 v[170:173], v137 offset:512
	ds_read_b128 v[174:177], v137 offset:576
	ds_read_b128 v[178:181], v137 offset:640
	ds_read_b128 v[182:185], v137 offset:704
	v_add_u32_e32 v211, s27, v144
	v_mul_lo_u32 v210, v211, s71
	v_add_u32_e32 v212, s28, v135
	v_lshl_add_u32 v210, v212, 1, v210
	s_waitcnt lgkmcnt(7)
	v_mul_f32_e32 v186, v116, v154
	v_mul_f32_e32 v187, v112, v154
	v_mul_f32_e32 v188, v124, v154
	v_mul_f32_e32 v189, v120, v154
	v_cvt_pk_bf16_f32 v202, v186, v187
	v_cvt_pk_bf16_f32 v203, v188, v189
	global_store_dwordx2 v210, v[202:203], s[46:47] sc1
	v_mul_f32_e32 v190, v117, v155
	v_mul_f32_e32 v191, v113, v155
	v_mul_f32_e32 v192, v125, v155
	v_mul_f32_e32 v193, v121, v155
	v_cvt_pk_bf16_f32 v204, v190, v191
	v_cvt_pk_bf16_f32 v205, v192, v193
	v_add_u32_e32 v211, 0x3000, v210
	global_store_dwordx2 v211, v[204:205], s[46:47] sc1
	v_mul_f32_e32 v194, v118, v156
	v_mul_f32_e32 v195, v114, v156
	v_mul_f32_e32 v196, v126, v156
	v_mul_f32_e32 v197, v122, v156
	v_cvt_pk_bf16_f32 v206, v194, v195
	v_cvt_pk_bf16_f32 v207, v196, v197
	v_add_u32_e32 v212, 0x6000, v210
	global_store_dwordx2 v212, v[206:207], s[46:47] sc1
	v_mul_f32_e32 v198, v119, v157
	v_mul_f32_e32 v199, v115, v157
	v_mul_f32_e32 v200, v127, v157
	v_mul_f32_e32 v201, v123, v157
	v_cvt_pk_bf16_f32 v208, v198, v199
	v_cvt_pk_bf16_f32 v209, v200, v201
	v_add_u32_e32 v211, 0x9000, v210
	global_store_dwordx2 v211, v[208:209], s[46:47] sc1
	s_waitcnt lgkmcnt(6)
	v_mul_f32_e32 v186, v100, v158
	v_mul_f32_e32 v187, v96, v158
	v_mul_f32_e32 v188, v108, v158
	v_mul_f32_e32 v189, v104, v158
	v_cvt_pk_bf16_f32 v202, v186, v187
	v_cvt_pk_bf16_f32 v203, v188, v189
	v_add_u32_e32 v212, 0x30000, v210
	global_store_dwordx2 v212, v[202:203], s[46:47] sc1
	v_mul_f32_e32 v190, v101, v159
	v_mul_f32_e32 v191, v97, v159
	v_mul_f32_e32 v192, v109, v159
	v_mul_f32_e32 v193, v105, v159
	v_cvt_pk_bf16_f32 v204, v190, v191
	v_cvt_pk_bf16_f32 v205, v192, v193
	v_add_u32_e32 v211, 0x33000, v210
	global_store_dwordx2 v211, v[204:205], s[46:47] sc1
	v_mul_f32_e32 v194, v102, v160
	v_mul_f32_e32 v195, v98, v160
	v_mul_f32_e32 v196, v110, v160
	v_mul_f32_e32 v197, v106, v160
	v_cvt_pk_bf16_f32 v206, v194, v195
	v_cvt_pk_bf16_f32 v207, v196, v197
	v_add_u32_e32 v212, 0x36000, v210
	global_store_dwordx2 v212, v[206:207], s[46:47] sc1
	v_mul_f32_e32 v198, v103, v161
	v_mul_f32_e32 v199, v99, v161
	v_mul_f32_e32 v200, v111, v161
	v_mul_f32_e32 v201, v107, v161
	v_cvt_pk_bf16_f32 v208, v198, v199
	v_cvt_pk_bf16_f32 v209, v200, v201
	v_add_u32_e32 v211, 0x39000, v210
	global_store_dwordx2 v211, v[208:209], s[46:47] sc1
	s_waitcnt lgkmcnt(5)
	v_mul_f32_e32 v186, v84, v162
	v_mul_f32_e32 v187, v80, v162
	v_mul_f32_e32 v188, v92, v162
	v_mul_f32_e32 v189, v88, v162
	v_cvt_pk_bf16_f32 v202, v186, v187
	v_cvt_pk_bf16_f32 v203, v188, v189
	v_add_u32_e32 v212, 0x60000, v210
	global_store_dwordx2 v212, v[202:203], s[46:47] sc1
	v_mul_f32_e32 v190, v85, v163
	v_mul_f32_e32 v191, v81, v163
	v_mul_f32_e32 v192, v93, v163
	v_mul_f32_e32 v193, v89, v163
	v_cvt_pk_bf16_f32 v204, v190, v191
	v_cvt_pk_bf16_f32 v205, v192, v193
	v_add_u32_e32 v211, 0x63000, v210
	global_store_dwordx2 v211, v[204:205], s[46:47] sc1
	v_mul_f32_e32 v194, v86, v164
	v_mul_f32_e32 v195, v82, v164
	v_mul_f32_e32 v196, v94, v164
	v_mul_f32_e32 v197, v90, v164
	v_cvt_pk_bf16_f32 v206, v194, v195
	v_cvt_pk_bf16_f32 v207, v196, v197
	v_add_u32_e32 v212, 0x66000, v210
	global_store_dwordx2 v212, v[206:207], s[46:47] sc1
	v_mul_f32_e32 v198, v87, v165
	v_mul_f32_e32 v199, v83, v165
	v_mul_f32_e32 v200, v95, v165
	v_mul_f32_e32 v201, v91, v165
	v_cvt_pk_bf16_f32 v208, v198, v199
	v_cvt_pk_bf16_f32 v209, v200, v201
	v_add_u32_e32 v211, 0x69000, v210
	global_store_dwordx2 v211, v[208:209], s[46:47] sc1
	s_waitcnt lgkmcnt(4)
	v_mul_f32_e32 v186, v60, v166
	v_mul_f32_e32 v187, v56, v166
	v_mul_f32_e32 v188, v76, v166
	v_mul_f32_e32 v189, v72, v166
	v_cvt_pk_bf16_f32 v202, v186, v187
	v_cvt_pk_bf16_f32 v203, v188, v189
	v_add_u32_e32 v212, 0x90000, v210
	global_store_dwordx2 v212, v[202:203], s[46:47] sc1
	v_mul_f32_e32 v190, v61, v167
	v_mul_f32_e32 v191, v57, v167
	v_mul_f32_e32 v192, v77, v167
	v_mul_f32_e32 v193, v73, v167
	v_cvt_pk_bf16_f32 v204, v190, v191
	v_cvt_pk_bf16_f32 v205, v192, v193
	v_add_u32_e32 v211, 0x93000, v210
	global_store_dwordx2 v211, v[204:205], s[46:47] sc1
	v_mul_f32_e32 v194, v62, v168
	v_mul_f32_e32 v195, v58, v168
	v_mul_f32_e32 v196, v78, v168
	v_mul_f32_e32 v197, v74, v168
	v_cvt_pk_bf16_f32 v206, v194, v195
	v_cvt_pk_bf16_f32 v207, v196, v197
	v_add_u32_e32 v212, 0x96000, v210
	global_store_dwordx2 v212, v[206:207], s[46:47] sc1
	v_mul_f32_e32 v198, v63, v169
	v_mul_f32_e32 v199, v59, v169
	v_mul_f32_e32 v200, v79, v169
	v_mul_f32_e32 v201, v75, v169
	v_cvt_pk_bf16_f32 v208, v198, v199
	v_cvt_pk_bf16_f32 v209, v200, v201
	v_add_u32_e32 v211, 0x99000, v210
	global_store_dwordx2 v211, v[208:209], s[46:47] sc1
	s_waitcnt lgkmcnt(3)
; template <int EPI, int N, int K>
; __device__ __forceinline__ void gemm_phase(const bf16_t* __restrict__ A, const bf16_t* __restrict__ Bt, const EpiArgs ea) {
;     ...
; #pragma unroll
;       for (int ai = 0; ai < 2; ++ai)
; #pragma unroll
;         for (int m = 0; m < 4; ++m) {
;           const f32x4 r4 = *(const f32x4*)(rstd_l + ai * 128 + wr * 64 + m * 16 + fq * 4);
; #pragma unroll
;           for (int j = 0; j < 4; ++j) {
;             const int row = brow + ai * 128 + wr * 64 + m * 16 + fq * 4 + j;
;             const float rs = r4[j];
;             float v0 = acc[ai][0][m][0][j] * rs, v1 = acc[ai][0][m][1][j] * rs, v2 = acc[ai][1][m][0][j] * rs, v3 = acc[ai][1][m][1][j] * rs;
;             if (EPI == EPI_MLP) {
;               v0 = fmaxf(v0, 0.f); v1 = fmaxf(v1, 0.f); v2 = fmaxf(v2, 0.f); v3 = fmaxf(v3, 0.f);
;               v0 *= v0; v1 *= v1; v2 *= v2; v3 *= v3;
;             }
;             u32x2 o = {pk2(v0, v1), pk2(v2, v3)};
;             st_wt(ea.outb + (size_t)row * N + c0, o);
;           }
;         }
	v_mul_f32_e32 v186, v52, v170
	v_mul_f32_e32 v187, v48, v170
	v_mul_f32_e32 v188, v68, v170
	v_mul_f32_e32 v189, v64, v170
	v_cvt_pk_bf16_f32 v202, v186, v187
	v_cvt_pk_bf16_f32 v203, v188, v189
	v_add_u32_e32 v212, 0x180000, v210
	global_store_dwordx2 v212, v[202:203], s[46:47] sc1
	v_mul_f32_e32 v190, v53, v171
	v_mul_f32_e32 v191, v49, v171
	v_mul_f32_e32 v192, v69, v171
	v_mul_f32_e32 v193, v65, v171
	v_cvt_pk_bf16_f32 v204, v190, v191
	v_cvt_pk_bf16_f32 v205, v192, v193
	v_add_u32_e32 v211, 0x183000, v210
	global_store_dwordx2 v211, v[204:205], s[46:47] sc1
	v_mul_f32_e32 v194, v54, v172
	v_mul_f32_e32 v195, v50, v172
	v_mul_f32_e32 v196, v70, v172
	v_mul_f32_e32 v197, v66, v172
	v_cvt_pk_bf16_f32 v206, v194, v195
	v_cvt_pk_bf16_f32 v207, v196, v197
	v_add_u32_e32 v212, 0x186000, v210
	global_store_dwordx2 v212, v[206:207], s[46:47] sc1
	v_mul_f32_e32 v198, v55, v173
	v_mul_f32_e32 v199, v51, v173
	v_mul_f32_e32 v200, v71, v173
	v_mul_f32_e32 v201, v67, v173
	v_cvt_pk_bf16_f32 v208, v198, v199
	v_cvt_pk_bf16_f32 v209, v200, v201
	v_add_u32_e32 v211, 0x189000, v210
	global_store_dwordx2 v211, v[208:209], s[46:47] sc1
	s_waitcnt lgkmcnt(2)
	v_mul_f32_e32 v186, v36, v174
	v_mul_f32_e32 v187, v32, v174
	v_mul_f32_e32 v188, v44, v174
	v_mul_f32_e32 v189, v40, v174
	v_cvt_pk_bf16_f32 v202, v186, v187
	v_cvt_pk_bf16_f32 v203, v188, v189
	v_add_u32_e32 v212, 0x1b0000, v210
	global_store_dwordx2 v212, v[202:203], s[46:47] sc1
	v_mul_f32_e32 v190, v37, v175
	v_mul_f32_e32 v191, v33, v175
	v_mul_f32_e32 v192, v45, v175
	v_mul_f32_e32 v193, v41, v175
	v_cvt_pk_bf16_f32 v204, v190, v191
	v_cvt_pk_bf16_f32 v205, v192, v193
	v_add_u32_e32 v211, 0x1b3000, v210
	global_store_dwordx2 v211, v[204:205], s[46:47] sc1
	v_mul_f32_e32 v194, v38, v176
	v_mul_f32_e32 v195, v34, v176
	v_mul_f32_e32 v196, v46, v176
	v_mul_f32_e32 v197, v42, v176
	v_cvt_pk_bf16_f32 v206, v194, v195
	v_cvt_pk_bf16_f32 v207, v196, v197
	v_add_u32_e32 v212, 0x1b6000, v210
	global_store_dwordx2 v212, v[206:207], s[46:47] sc1
	v_mul_f32_e32 v198, v39, v177
	v_mul_f32_e32 v199, v35, v177
	v_mul_f32_e32 v200, v47, v177
	v_mul_f32_e32 v201, v43, v177
	v_cvt_pk_bf16_f32 v208, v198, v199
	v_cvt_pk_bf16_f32 v209, v200, v201
	v_add_u32_e32 v211, 0x1b9000, v210
	global_store_dwordx2 v211, v[208:209], s[46:47] sc1
	s_waitcnt lgkmcnt(1)
	v_mul_f32_e32 v186, v20, v178
	v_mul_f32_e32 v187, v16, v178
	v_mul_f32_e32 v188, v28, v178
	v_mul_f32_e32 v189, v24, v178
	v_cvt_pk_bf16_f32 v202, v186, v187
	v_cvt_pk_bf16_f32 v203, v188, v189
	v_add_u32_e32 v212, 0x1e0000, v210
	global_store_dwordx2 v212, v[202:203], s[46:47] sc1
	v_mul_f32_e32 v190, v21, v179
	v_mul_f32_e32 v191, v17, v179
	v_mul_f32_e32 v192, v29, v179
	v_mul_f32_e32 v193, v25, v179
	v_cvt_pk_bf16_f32 v204, v190, v191
	v_cvt_pk_bf16_f32 v205, v192, v193
	v_add_u32_e32 v211, 0x1e3000, v210
	global_store_dwordx2 v211, v[204:205], s[46:47] sc1
	v_mul_f32_e32 v194, v22, v180
	v_mul_f32_e32 v195, v18, v180
	v_mul_f32_e32 v196, v30, v180
	v_mul_f32_e32 v197, v26, v180
	v_cvt_pk_bf16_f32 v206, v194, v195
	v_cvt_pk_bf16_f32 v207, v196, v197
	v_add_u32_e32 v212, 0x1e6000, v210
	global_store_dwordx2 v212, v[206:207], s[46:47] sc1
	v_mul_f32_e32 v198, v23, v181
	v_mul_f32_e32 v199, v19, v181
	v_mul_f32_e32 v200, v31, v181
	v_mul_f32_e32 v201, v27, v181
	v_cvt_pk_bf16_f32 v208, v198, v199
	v_cvt_pk_bf16_f32 v209, v200, v201
	v_add_u32_e32 v211, 0x1e9000, v210
	global_store_dwordx2 v211, v[208:209], s[46:47] sc1
	s_waitcnt lgkmcnt(0)
	v_mul_f32_e32 v186, v4, v182
	v_mul_f32_e32 v187, v0, v182
	v_mul_f32_e32 v188, v12, v182
	v_mul_f32_e32 v189, v8, v182
	v_cvt_pk_bf16_f32 v202, v186, v187
	v_cvt_pk_bf16_f32 v203, v188, v189
	v_add_u32_e32 v212, 0x210000, v210
	global_store_dwordx2 v212, v[202:203], s[46:47] sc1
	v_mul_f32_e32 v190, v5, v183
	v_mul_f32_e32 v191, v1, v183
	v_mul_f32_e32 v192, v13, v183
	v_mul_f32_e32 v193, v9, v183
	v_cvt_pk_bf16_f32 v204, v190, v191
	v_cvt_pk_bf16_f32 v205, v192, v193
	v_add_u32_e32 v211, 0x213000, v210
	global_store_dwordx2 v211, v[204:205], s[46:47] sc1
	v_mul_f32_e32 v194, v6, v184
	v_mul_f32_e32 v195, v2, v184
	v_mul_f32_e32 v196, v14, v184
	v_mul_f32_e32 v197, v10, v184
	v_cvt_pk_bf16_f32 v206, v194, v195
	v_cvt_pk_bf16_f32 v207, v196, v197
	v_add_u32_e32 v212, 0x216000, v210
	global_store_dwordx2 v212, v[206:207], s[46:47] sc1
	v_mul_f32_e32 v198, v7, v185
	v_mul_f32_e32 v199, v3, v185
	v_mul_f32_e32 v200, v15, v185
	v_mul_f32_e32 v201, v11, v185
	v_cvt_pk_bf16_f32 v208, v198, v199
	v_cvt_pk_bf16_f32 v209, v200, v201
	v_add_u32_e32 v211, 0x219000, v210
	global_store_dwordx2 v211, v[208:209], s[46:47] sc1
	s_andn2_b64 vcc, exec, s[0:1]
	s_cbranch_vccz .LBB0_142

; #define BAR __builtin_amdgcn_s_barrier()
; template <int EPI, int N, int K>
; __device__ __forceinline__ void gemm_phase(const bf16_t* __restrict__ A, const bf16_t* __restrict__ Bt, const EpiArgs ea) {
;     ...
;       asm volatile("s_waitcnt lgkmcnt(0)" ::: "memory"); BAR;
; #pragma unroll
;       for (int ai = 0; ai < 2; ++ai)
; #pragma unroll
;         for (int m = 0; m < 4; ++m) {
;           const f32x4 r4 = *(const f32x4*)(rstd_l + ai * 128 + wr * 64 + m * 16 + fq * 4);
; #pragma unroll
;           for (int j = 0; j < 4; ++j) {
;             const int row = brow + ai * 128 + wr * 64 + m * 16 + fq * 4 + j;
;             const float rs = r4[j];
;             float v0 = acc[ai][0][m][0][j] * rs, v1 = acc[ai][0][m][1][j] * rs, v2 = acc[ai][1][m][0][j] * rs, v3 = acc[ai][1][m][1][j] * rs;
;             if (EPI == EPI_MLP) {
;               v0 = fmaxf(v0, 0.f); v1 = fmaxf(v1, 0.f); v2 = fmaxf(v2, 0.f); v3 = fmaxf(v3, 0.f);
;               v0 *= v0; v1 *= v1; v2 *= v2; v3 *= v3;
;             }
;             u32x2 o = {pk2(v0, v1), pk2(v2, v3)};
;             st_wt(ea.outb + (size_t)row * N + c0, o);
;           }
;         }
.LBB0_264:
	s_or_b64 exec, exec, s[2:3]
	s_waitcnt lgkmcnt(0)
	s_barrier
	ds_read_b128 v[154:157], v137
	ds_read_b128 v[158:161], v137 offset:64
	ds_read_b128 v[162:165], v137 offset:128
	ds_read_b128 v[166:169], v137 offset:192
	ds_read_b128 v[170:173], v137 offset:512
	ds_read_b128 v[174:177], v137 offset:576
	ds_read_b128 v[178:181], v137 offset:640
	ds_read_b128 v[182:185], v137 offset:704
	v_add_u32_e32 v211, s27, v144
	v_mul_lo_u32 v210, v211, s55
	v_add_u32_e32 v212, s28, v135
	v_lshl_add_u32 v210, v212, 1, v210
	s_waitcnt lgkmcnt(7)
	v_mul_f32_e32 v186, v116, v154
	v_mul_f32_e32 v187, v112, v154
	v_mul_f32_e32 v188, v124, v154
	v_mul_f32_e32 v189, v120, v154
	v_cvt_pk_bf16_f32 v202, v186, v187
	v_cvt_pk_bf16_f32 v203, v188, v189
	global_store_dwordx2 v210, v[202:203], s[46:47] sc1
	v_mul_f32_e32 v190, v117, v155
	v_mul_f32_e32 v191, v113, v155
	v_mul_f32_e32 v192, v125, v155
	v_mul_f32_e32 v193, v121, v155
	v_cvt_pk_bf16_f32 v204, v190, v191
	v_cvt_pk_bf16_f32 v205, v192, v193
	v_add_u32_e32 v211, 0x1400, v210
	global_store_dwordx2 v211, v[204:205], s[46:47] sc1
	v_mul_f32_e32 v194, v118, v156
	v_mul_f32_e32 v195, v114, v156
	v_mul_f32_e32 v196, v126, v156
	v_mul_f32_e32 v197, v122, v156
	v_cvt_pk_bf16_f32 v206, v194, v195
	v_cvt_pk_bf16_f32 v207, v196, v197
	v_add_u32_e32 v212, 0x2800, v210
	global_store_dwordx2 v212, v[206:207], s[46:47] sc1
	v_mul_f32_e32 v198, v119, v157
	v_mul_f32_e32 v199, v115, v157
	v_mul_f32_e32 v200, v127, v157
	v_mul_f32_e32 v201, v123, v157
	v_cvt_pk_bf16_f32 v208, v198, v199
	v_cvt_pk_bf16_f32 v209, v200, v201
	v_add_u32_e32 v211, 0x3c00, v210
	global_store_dwordx2 v211, v[208:209], s[46:47] sc1
	s_waitcnt lgkmcnt(6)
	v_mul_f32_e32 v186, v100, v158
	v_mul_f32_e32 v187, v96, v158
	v_mul_f32_e32 v188, v108, v158
	v_mul_f32_e32 v189, v104, v158
	v_cvt_pk_bf16_f32 v202, v186, v187
	v_cvt_pk_bf16_f32 v203, v188, v189
	v_add_u32_e32 v212, 0x14000, v210
	global_store_dwordx2 v212, v[202:203], s[46:47] sc1
	v_mul_f32_e32 v190, v101, v159
	v_mul_f32_e32 v191, v97, v159
	v_mul_f32_e32 v192, v109, v159
	v_mul_f32_e32 v193, v105, v159
	v_cvt_pk_bf16_f32 v204, v190, v191
	v_cvt_pk_bf16_f32 v205, v192, v193
	v_add_u32_e32 v211, 0x15400, v210
	global_store_dwordx2 v211, v[204:205], s[46:47] sc1
	v_mul_f32_e32 v194, v102, v160
	v_mul_f32_e32 v195, v98, v160
	v_mul_f32_e32 v196, v110, v160
	v_mul_f32_e32 v197, v106, v160
	v_cvt_pk_bf16_f32 v206, v194, v195
	v_cvt_pk_bf16_f32 v207, v196, v197
	v_add_u32_e32 v212, 0x16800, v210
	global_store_dwordx2 v212, v[206:207], s[46:47] sc1
	v_mul_f32_e32 v198, v103, v161
	v_mul_f32_e32 v199, v99, v161
	v_mul_f32_e32 v200, v111, v161
	v_mul_f32_e32 v201, v107, v161
	v_cvt_pk_bf16_f32 v208, v198, v199
	v_cvt_pk_bf16_f32 v209, v200, v201
	v_add_u32_e32 v211, 0x17c00, v210
	global_store_dwordx2 v211, v[208:209], s[46:47] sc1
	s_waitcnt lgkmcnt(5)
	v_mul_f32_e32 v186, v84, v162
	v_mul_f32_e32 v187, v80, v162
	v_mul_f32_e32 v188, v92, v162
	v_mul_f32_e32 v189, v88, v162
	v_cvt_pk_bf16_f32 v202, v186, v187
	v_cvt_pk_bf16_f32 v203, v188, v189
	v_add_u32_e32 v212, 0x28000, v210
	global_store_dwordx2 v212, v[202:203], s[46:47] sc1
	v_mul_f32_e32 v190, v85, v163
	v_mul_f32_e32 v191, v81, v163
	v_mul_f32_e32 v192, v93, v163
	v_mul_f32_e32 v193, v89, v163
	v_cvt_pk_bf16_f32 v204, v190, v191
	v_cvt_pk_bf16_f32 v205, v192, v193
	v_add_u32_e32 v211, 0x29400, v210
	global_store_dwordx2 v211, v[204:205], s[46:47] sc1
	v_mul_f32_e32 v194, v86, v164
	v_mul_f32_e32 v195, v82, v164
	v_mul_f32_e32 v196, v94, v164
	v_mul_f32_e32 v197, v90, v164
	v_cvt_pk_bf16_f32 v206, v194, v195
	v_cvt_pk_bf16_f32 v207, v196, v197
	v_add_u32_e32 v212, 0x2a800, v210
	global_store_dwordx2 v212, v[206:207], s[46:47] sc1
	v_mul_f32_e32 v198, v87, v165
	v_mul_f32_e32 v199, v83, v165
	v_mul_f32_e32 v200, v95, v165
	v_mul_f32_e32 v201, v91, v165
	v_cvt_pk_bf16_f32 v208, v198, v199
	v_cvt_pk_bf16_f32 v209, v200, v201
	v_add_u32_e32 v211, 0x2bc00, v210
	global_store_dwordx2 v211, v[208:209], s[46:47] sc1
	s_waitcnt lgkmcnt(4)
	v_mul_f32_e32 v186, v60, v166
	v_mul_f32_e32 v187, v56, v166
	v_mul_f32_e32 v188, v76, v166
	v_mul_f32_e32 v189, v72, v166
	v_cvt_pk_bf16_f32 v202, v186, v187
	v_cvt_pk_bf16_f32 v203, v188, v189
	v_add_u32_e32 v212, 0x3c000, v210
	global_store_dwordx2 v212, v[202:203], s[46:47] sc1
	v_mul_f32_e32 v190, v61, v167
	v_mul_f32_e32 v191, v57, v167
	v_mul_f32_e32 v192, v77, v167
	v_mul_f32_e32 v193, v73, v167
	v_cvt_pk_bf16_f32 v204, v190, v191
	v_cvt_pk_bf16_f32 v205, v192, v193
	v_add_u32_e32 v211, 0x3d400, v210
	global_store_dwordx2 v211, v[204:205], s[46:47] sc1
	v_mul_f32_e32 v194, v62, v168
	v_mul_f32_e32 v195, v58, v168
	v_mul_f32_e32 v196, v78, v168
	v_mul_f32_e32 v197, v74, v168
	v_cvt_pk_bf16_f32 v206, v194, v195
	v_cvt_pk_bf16_f32 v207, v196, v197
	v_add_u32_e32 v212, 0x3e800, v210
	global_store_dwordx2 v212, v[206:207], s[46:47] sc1
	v_mul_f32_e32 v198, v63, v169
	v_mul_f32_e32 v199, v59, v169
	v_mul_f32_e32 v200, v79, v169
	v_mul_f32_e32 v201, v75, v169
	v_cvt_pk_bf16_f32 v208, v198, v199
	v_cvt_pk_bf16_f32 v209, v200, v201
	v_add_u32_e32 v211, 0x3fc00, v210
	global_store_dwordx2 v211, v[208:209], s[46:47] sc1
	s_waitcnt lgkmcnt(3)
; template <int EPI, int N, int K>
; __device__ __forceinline__ void gemm_phase(const bf16_t* __restrict__ A, const bf16_t* __restrict__ Bt, const EpiArgs ea) {
;     ...
; #pragma unroll
;       for (int ai = 0; ai < 2; ++ai)
; #pragma unroll
;         for (int m = 0; m < 4; ++m) {
;           const f32x4 r4 = *(const f32x4*)(rstd_l + ai * 128 + wr * 64 + m * 16 + fq * 4);
; #pragma unroll
;           for (int j = 0; j < 4; ++j) {
;             const int row = brow + ai * 128 + wr * 64 + m * 16 + fq * 4 + j;
;             const float rs = r4[j];
;             float v0 = acc[ai][0][m][0][j] * rs, v1 = acc[ai][0][m][1][j] * rs, v2 = acc[ai][1][m][0][j] * rs, v3 = acc[ai][1][m][1][j] * rs;
;             if (EPI == EPI_MLP) {
;               v0 = fmaxf(v0, 0.f); v1 = fmaxf(v1, 0.f); v2 = fmaxf(v2, 0.f); v3 = fmaxf(v3, 0.f);
;               v0 *= v0; v1 *= v1; v2 *= v2; v3 *= v3;
;             }
;             u32x2 o = {pk2(v0, v1), pk2(v2, v3)};
;             st_wt(ea.outb + (size_t)row * N + c0, o);
;           }
;         }
	v_mul_f32_e32 v186, v52, v170
	v_mul_f32_e32 v187, v48, v170
	v_mul_f32_e32 v188, v68, v170
	v_mul_f32_e32 v189, v64, v170
	v_cvt_pk_bf16_f32 v202, v186, v187
	v_cvt_pk_bf16_f32 v203, v188, v189
	v_add_u32_e32 v212, 0xa0000, v210
	global_store_dwordx2 v212, v[202:203], s[46:47] sc1
	v_mul_f32_e32 v190, v53, v171
	v_mul_f32_e32 v191, v49, v171
	v_mul_f32_e32 v192, v69, v171
	v_mul_f32_e32 v193, v65, v171
	v_cvt_pk_bf16_f32 v204, v190, v191
	v_cvt_pk_bf16_f32 v205, v192, v193
	v_add_u32_e32 v211, 0xa1400, v210
	global_store_dwordx2 v211, v[204:205], s[46:47] sc1
	v_mul_f32_e32 v194, v54, v172
	v_mul_f32_e32 v195, v50, v172
	v_mul_f32_e32 v196, v70, v172
	v_mul_f32_e32 v197, v66, v172
	v_cvt_pk_bf16_f32 v206, v194, v195
	v_cvt_pk_bf16_f32 v207, v196, v197
	v_add_u32_e32 v212, 0xa2800, v210
	global_store_dwordx2 v212, v[206:207], s[46:47] sc1
	v_mul_f32_e32 v198, v55, v173
	v_mul_f32_e32 v199, v51, v173
	v_mul_f32_e32 v200, v71, v173
	v_mul_f32_e32 v201, v67, v173
	v_cvt_pk_bf16_f32 v208, v198, v199
	v_cvt_pk_bf16_f32 v209, v200, v201
	v_add_u32_e32 v211, 0xa3c00, v210
	global_store_dwordx2 v211, v[208:209], s[46:47] sc1
	s_waitcnt lgkmcnt(2)
	v_mul_f32_e32 v186, v36, v174
	v_mul_f32_e32 v187, v32, v174
	v_mul_f32_e32 v188, v44, v174
	v_mul_f32_e32 v189, v40, v174
	v_cvt_pk_bf16_f32 v202, v186, v187
	v_cvt_pk_bf16_f32 v203, v188, v189
	v_add_u32_e32 v212, 0xb4000, v210
	global_store_dwordx2 v212, v[202:203], s[46:47] sc1
	v_mul_f32_e32 v190, v37, v175
	v_mul_f32_e32 v191, v33, v175
	v_mul_f32_e32 v192, v45, v175
	v_mul_f32_e32 v193, v41, v175
	v_cvt_pk_bf16_f32 v204, v190, v191
	v_cvt_pk_bf16_f32 v205, v192, v193
	v_add_u32_e32 v211, 0xb5400, v210
	global_store_dwordx2 v211, v[204:205], s[46:47] sc1
	v_mul_f32_e32 v194, v38, v176
	v_mul_f32_e32 v195, v34, v176
	v_mul_f32_e32 v196, v46, v176
	v_mul_f32_e32 v197, v42, v176
	v_cvt_pk_bf16_f32 v206, v194, v195
	v_cvt_pk_bf16_f32 v207, v196, v197
	v_add_u32_e32 v212, 0xb6800, v210
	global_store_dwordx2 v212, v[206:207], s[46:47] sc1
	v_mul_f32_e32 v198, v39, v177
	v_mul_f32_e32 v199, v35, v177
	v_mul_f32_e32 v200, v47, v177
	v_mul_f32_e32 v201, v43, v177
	v_cvt_pk_bf16_f32 v208, v198, v199
	v_cvt_pk_bf16_f32 v209, v200, v201
	v_add_u32_e32 v211, 0xb7c00, v210
	global_store_dwordx2 v211, v[208:209], s[46:47] sc1
	s_waitcnt lgkmcnt(1)
	v_mul_f32_e32 v186, v20, v178
	v_mul_f32_e32 v187, v16, v178
	v_mul_f32_e32 v188, v28, v178
	v_mul_f32_e32 v189, v24, v178
	v_cvt_pk_bf16_f32 v202, v186, v187
	v_cvt_pk_bf16_f32 v203, v188, v189
	v_add_u32_e32 v212, 0xc8000, v210
	global_store_dwordx2 v212, v[202:203], s[46:47] sc1
	v_mul_f32_e32 v190, v21, v179
	v_mul_f32_e32 v191, v17, v179
	v_mul_f32_e32 v192, v29, v179
	v_mul_f32_e32 v193, v25, v179
	v_cvt_pk_bf16_f32 v204, v190, v191
	v_cvt_pk_bf16_f32 v205, v192, v193
	v_add_u32_e32 v211, 0xc9400, v210
	global_store_dwordx2 v211, v[204:205], s[46:47] sc1
	v_mul_f32_e32 v194, v22, v180
	v_mul_f32_e32 v195, v18, v180
	v_mul_f32_e32 v196, v30, v180
	v_mul_f32_e32 v197, v26, v180
	v_cvt_pk_bf16_f32 v206, v194, v195
	v_cvt_pk_bf16_f32 v207, v196, v197
	v_add_u32_e32 v212, 0xca800, v210
	global_store_dwordx2 v212, v[206:207], s[46:47] sc1
	v_mul_f32_e32 v198, v23, v181
	v_mul_f32_e32 v199, v19, v181
	v_mul_f32_e32 v200, v31, v181
	v_mul_f32_e32 v201, v27, v181
	v_cvt_pk_bf16_f32 v208, v198, v199
	v_cvt_pk_bf16_f32 v209, v200, v201
	v_add_u32_e32 v211, 0xcbc00, v210
	global_store_dwordx2 v211, v[208:209], s[46:47] sc1
	s_waitcnt lgkmcnt(0)
	v_mul_f32_e32 v186, v4, v182
	v_mul_f32_e32 v187, v0, v182
	v_mul_f32_e32 v188, v12, v182
	v_mul_f32_e32 v189, v8, v182
	v_cvt_pk_bf16_f32 v202, v186, v187
	v_cvt_pk_bf16_f32 v203, v188, v189
	v_add_u32_e32 v212, 0xdc000, v210
	global_store_dwordx2 v212, v[202:203], s[46:47] sc1
	v_mul_f32_e32 v190, v5, v183
	v_mul_f32_e32 v191, v1, v183
	v_mul_f32_e32 v192, v13, v183
	v_mul_f32_e32 v193, v9, v183
	v_cvt_pk_bf16_f32 v204, v190, v191
	v_cvt_pk_bf16_f32 v205, v192, v193
	v_add_u32_e32 v211, 0xdd400, v210
	global_store_dwordx2 v211, v[204:205], s[46:47] sc1
	v_mul_f32_e32 v194, v6, v184
	v_mul_f32_e32 v195, v2, v184
	v_mul_f32_e32 v196, v14, v184
	v_mul_f32_e32 v197, v10, v184
	v_cvt_pk_bf16_f32 v206, v194, v195
	v_cvt_pk_bf16_f32 v207, v196, v197
	v_add_u32_e32 v212, 0xde800, v210
	global_store_dwordx2 v212, v[206:207], s[46:47] sc1
	v_mul_f32_e32 v198, v7, v185
	v_mul_f32_e32 v199, v3, v185
	v_mul_f32_e32 v200, v15, v185
	v_mul_f32_e32 v201, v11, v185
	v_cvt_pk_bf16_f32 v208, v198, v199
	v_cvt_pk_bf16_f32 v209, v200, v201
	v_add_u32_e32 v211, 0xdfc00, v210
	global_store_dwordx2 v211, v[208:209], s[46:47] sc1
	s_andn2_b64 vcc, exec, s[0:1]
	s_cbranch_vccz .LBB0_281

; #define BAR __builtin_amdgcn_s_barrier()
; template <int EPI, int N, int K>
; __device__ __forceinline__ void gemm_phase(const bf16_t* __restrict__ A, const bf16_t* __restrict__ Bt, const EpiArgs ea) {
;     ...
;       asm volatile("s_waitcnt lgkmcnt(0)" ::: "memory"); BAR;
; #pragma unroll
;       for (int ai = 0; ai < 2; ++ai)
; #pragma unroll
;         for (int m = 0; m < 4; ++m) {
;           const f32x4 r4 = *(const f32x4*)(rstd_l + ai * 128 + wr * 64 + m * 16 + fq * 4);
; #pragma unroll
;           for (int j = 0; j < 4; ++j) {
;             const int row = brow + ai * 128 + wr * 64 + m * 16 + fq * 4 + j;
;             const float rs = r4[j];
;             float v0 = acc[ai][0][m][0][j] * rs, v1 = acc[ai][0][m][1][j] * rs, v2 = acc[ai][1][m][0][j] * rs, v3 = acc[ai][1][m][1][j] * rs;
;             if (EPI == EPI_MLP) {
;               v0 = fmaxf(v0, 0.f); v1 = fmaxf(v1, 0.f); v2 = fmaxf(v2, 0.f); v3 = fmaxf(v3, 0.f);
;               v0 *= v0; v1 *= v1; v2 *= v2; v3 *= v3;
;             }
;             u32x2 o = {pk2(v0, v1), pk2(v2, v3)};
;             st_wt(ea.outb + (size_t)row * N + c0, o);
;           }
;         }
.LBB0_503:
	s_or_b64 exec, exec, s[2:3]
	s_waitcnt lgkmcnt(0)
	s_barrier
	ds_read_b128 v[156:159], v146
	ds_read_b128 v[160:163], v146 offset:64
	ds_read_b128 v[164:167], v146 offset:128
	ds_read_b128 v[168:171], v146 offset:192
	ds_read_b128 v[172:175], v146 offset:512
	ds_read_b128 v[176:179], v146 offset:576
	ds_read_b128 v[180:183], v146 offset:640
	ds_read_b128 v[184:187], v146 offset:704
	v_add_u32_e32 v213, s34, v147
	v_lshlrev_b32_e32 v212, 14, v213
	v_add_u32_e32 v214, s35, v144
	v_lshl_add_u32 v212, v214, 1, v212
	s_waitcnt lgkmcnt(7)
	v_mul_f32_e32 v188, v112, v156
	v_mul_f32_e32 v189, v116, v156
	v_mul_f32_e32 v190, v120, v156
	v_mul_f32_e32 v191, v124, v156
	v_max_f32_e32 v188, 0, v188
	v_max_f32_e32 v189, 0, v189
	v_max_f32_e32 v190, 0, v190
	v_max_f32_e32 v191, 0, v191
	v_pk_mul_f32 v[188:189], v[188:189], v[188:189]
	v_pk_mul_f32 v[190:191], v[190:191], v[190:191]
	v_cvt_pk_bf16_f32 v204, v188, v189
	v_cvt_pk_bf16_f32 v205, v190, v191
	global_store_dwordx2 v212, v[204:205], s[46:47] sc1
	v_mul_f32_e32 v192, v113, v157
	v_mul_f32_e32 v193, v117, v157
	v_mul_f32_e32 v194, v121, v157
	v_mul_f32_e32 v195, v125, v157
	v_max_f32_e32 v192, 0, v192
	v_max_f32_e32 v193, 0, v193
	v_max_f32_e32 v194, 0, v194
	v_max_f32_e32 v195, 0, v195
	v_pk_mul_f32 v[192:193], v[192:193], v[192:193]
	v_pk_mul_f32 v[194:195], v[194:195], v[194:195]
	v_cvt_pk_bf16_f32 v206, v192, v193
	v_cvt_pk_bf16_f32 v207, v194, v195
	v_add_u32_e32 v213, 0x4000, v212
	global_store_dwordx2 v213, v[206:207], s[46:47] sc1
	v_mul_f32_e32 v196, v114, v158
	v_mul_f32_e32 v197, v118, v158
	v_mul_f32_e32 v198, v122, v158
	v_mul_f32_e32 v199, v126, v158
	v_max_f32_e32 v196, 0, v196
	v_max_f32_e32 v197, 0, v197
	v_max_f32_e32 v198, 0, v198
	v_max_f32_e32 v199, 0, v199
	v_pk_mul_f32 v[196:197], v[196:197], v[196:197]
	v_pk_mul_f32 v[198:199], v[198:199], v[198:199]
	v_cvt_pk_bf16_f32 v208, v196, v197
	v_cvt_pk_bf16_f32 v209, v198, v199
	v_add_u32_e32 v214, 0x8000, v212
	global_store_dwordx2 v214, v[208:209], s[46:47] sc1
	v_mul_f32_e32 v200, v115, v159
	v_mul_f32_e32 v201, v119, v159
	v_mul_f32_e32 v202, v123, v159
	v_mul_f32_e32 v203, v127, v159
	v_max_f32_e32 v200, 0, v200
	v_max_f32_e32 v201, 0, v201
	v_max_f32_e32 v202, 0, v202
	v_max_f32_e32 v203, 0, v203
	v_pk_mul_f32 v[200:201], v[200:201], v[200:201]
	v_pk_mul_f32 v[202:203], v[202:203], v[202:203]
	v_cvt_pk_bf16_f32 v210, v200, v201
	v_cvt_pk_bf16_f32 v211, v202, v203
	v_add_u32_e32 v213, 0xc000, v212
	global_store_dwordx2 v213, v[210:211], s[46:47] sc1
	s_waitcnt lgkmcnt(6)
	v_mul_f32_e32 v188, v96, v160
	v_mul_f32_e32 v189, v100, v160
	v_mul_f32_e32 v190, v104, v160
	v_mul_f32_e32 v191, v108, v160
	v_max_f32_e32 v188, 0, v188
	v_max_f32_e32 v189, 0, v189
	v_max_f32_e32 v190, 0, v190
	v_max_f32_e32 v191, 0, v191
	v_pk_mul_f32 v[188:189], v[188:189], v[188:189]
	v_pk_mul_f32 v[190:191], v[190:191], v[190:191]
	v_cvt_pk_bf16_f32 v204, v188, v189
	v_cvt_pk_bf16_f32 v205, v190, v191
	v_add_u32_e32 v214, 0x40000, v212
	global_store_dwordx2 v214, v[204:205], s[46:47] sc1
	v_mul_f32_e32 v192, v97, v161
	v_mul_f32_e32 v193, v101, v161
	v_mul_f32_e32 v194, v105, v161
	v_mul_f32_e32 v195, v109, v161
	v_max_f32_e32 v192, 0, v192
	v_max_f32_e32 v193, 0, v193
	v_max_f32_e32 v194, 0, v194
	v_max_f32_e32 v195, 0, v195
	v_pk_mul_f32 v[192:193], v[192:193], v[192:193]
	v_pk_mul_f32 v[194:195], v[194:195], v[194:195]
	v_cvt_pk_bf16_f32 v206, v192, v193
	v_cvt_pk_bf16_f32 v207, v194, v195
	v_add_u32_e32 v213, 0x44000, v212
	global_store_dwordx2 v213, v[206:207], s[46:47] sc1
	v_mul_f32_e32 v196, v98, v162
	v_mul_f32_e32 v197, v102, v162
	v_mul_f32_e32 v198, v106, v162
	v_mul_f32_e32 v199, v110, v162
	v_max_f32_e32 v196, 0, v196
	v_max_f32_e32 v197, 0, v197
	v_max_f32_e32 v198, 0, v198
	v_max_f32_e32 v199, 0, v199
	v_pk_mul_f32 v[196:197], v[196:197], v[196:197]
	v_pk_mul_f32 v[198:199], v[198:199], v[198:199]
	v_cvt_pk_bf16_f32 v208, v196, v197
	v_cvt_pk_bf16_f32 v209, v198, v199
	v_add_u32_e32 v214, 0x48000, v212
	global_store_dwordx2 v214, v[208:209], s[46:47] sc1
	v_mul_f32_e32 v200, v99, v163
	v_mul_f32_e32 v201, v103, v163
	v_mul_f32_e32 v202, v107, v163
	v_mul_f32_e32 v203, v111, v163
	v_max_f32_e32 v200, 0, v200
	v_max_f32_e32 v201, 0, v201
	v_max_f32_e32 v202, 0, v202
	v_max_f32_e32 v203, 0, v203
	v_pk_mul_f32 v[200:201], v[200:201], v[200:201]
	v_pk_mul_f32 v[202:203], v[202:203], v[202:203]
	v_cvt_pk_bf16_f32 v210, v200, v201
	v_cvt_pk_bf16_f32 v211, v202, v203
	v_add_u32_e32 v213, 0x4c000, v212
	global_store_dwordx2 v213, v[210:211], s[46:47] sc1
	s_waitcnt lgkmcnt(5)
	v_mul_f32_e32 v188, v80, v164
	v_mul_f32_e32 v189, v84, v164
	v_mul_f32_e32 v190, v88, v164
	v_mul_f32_e32 v191, v92, v164
	v_max_f32_e32 v188, 0, v188
	v_max_f32_e32 v189, 0, v189
	v_max_f32_e32 v190, 0, v190
	v_max_f32_e32 v191, 0, v191
	v_pk_mul_f32 v[188:189], v[188:189], v[188:189]
	v_pk_mul_f32 v[190:191], v[190:191], v[190:191]
	v_cvt_pk_bf16_f32 v204, v188, v189
	v_cvt_pk_bf16_f32 v205, v190, v191
	v_add_u32_e32 v214, 0x80000, v212
	global_store_dwordx2 v214, v[204:205], s[46:47] sc1
	v_mul_f32_e32 v192, v81, v165
	v_mul_f32_e32 v193, v85, v165
	v_mul_f32_e32 v194, v89, v165
	v_mul_f32_e32 v195, v93, v165
	v_max_f32_e32 v192, 0, v192
	v_max_f32_e32 v193, 0, v193
	v_max_f32_e32 v194, 0, v194
	v_max_f32_e32 v195, 0, v195
	v_pk_mul_f32 v[192:193], v[192:193], v[192:193]
	v_pk_mul_f32 v[194:195], v[194:195], v[194:195]
	v_cvt_pk_bf16_f32 v206, v192, v193
	v_cvt_pk_bf16_f32 v207, v194, v195
	v_add_u32_e32 v213, 0x84000, v212
	global_store_dwordx2 v213, v[206:207], s[46:47] sc1
	v_mul_f32_e32 v196, v82, v166
	v_mul_f32_e32 v197, v86, v166
	v_mul_f32_e32 v198, v90, v166
	v_mul_f32_e32 v199, v94, v166
	v_max_f32_e32 v196, 0, v196
	v_max_f32_e32 v197, 0, v197
	v_max_f32_e32 v198, 0, v198
	v_max_f32_e32 v199, 0, v199
	v_pk_mul_f32 v[196:197], v[196:197], v[196:197]
	v_pk_mul_f32 v[198:199], v[198:199], v[198:199]
	v_cvt_pk_bf16_f32 v208, v196, v197
	v_cvt_pk_bf16_f32 v209, v198, v199
	v_add_u32_e32 v214, 0x88000, v212
	global_store_dwordx2 v214, v[208:209], s[46:47] sc1
	v_mul_f32_e32 v200, v83, v167
	v_mul_f32_e32 v201, v87, v167
	v_mul_f32_e32 v202, v91, v167
	v_mul_f32_e32 v203, v95, v167
	v_max_f32_e32 v200, 0, v200
	v_max_f32_e32 v201, 0, v201
	v_max_f32_e32 v202, 0, v202
	v_max_f32_e32 v203, 0, v203
	v_pk_mul_f32 v[200:201], v[200:201], v[200:201]
	v_pk_mul_f32 v[202:203], v[202:203], v[202:203]
	v_cvt_pk_bf16_f32 v210, v200, v201
	v_cvt_pk_bf16_f32 v211, v202, v203
	v_add_u32_e32 v213, 0x8c000, v212
	global_store_dwordx2 v213, v[210:211], s[46:47] sc1
	s_waitcnt lgkmcnt(4)
; template <int EPI, int N, int K>
; __device__ __forceinline__ void gemm_phase(const bf16_t* __restrict__ A, const bf16_t* __restrict__ Bt, const EpiArgs ea) {
;     ...
; #pragma unroll
;       for (int ai = 0; ai < 2; ++ai)
; #pragma unroll
;         for (int m = 0; m < 4; ++m) {
;           const f32x4 r4 = *(const f32x4*)(rstd_l + ai * 128 + wr * 64 + m * 16 + fq * 4);
; #pragma unroll
;           for (int j = 0; j < 4; ++j) {
;             const int row = brow + ai * 128 + wr * 64 + m * 16 + fq * 4 + j;
;             const float rs = r4[j];
;             float v0 = acc[ai][0][m][0][j] * rs, v1 = acc[ai][0][m][1][j] * rs, v2 = acc[ai][1][m][0][j] * rs, v3 = acc[ai][1][m][1][j] * rs;
;             if (EPI == EPI_MLP) {
;               v0 = fmaxf(v0, 0.f); v1 = fmaxf(v1, 0.f); v2 = fmaxf(v2, 0.f); v3 = fmaxf(v3, 0.f);
;               v0 *= v0; v1 *= v1; v2 *= v2; v3 *= v3;
;             }
;             u32x2 o = {pk2(v0, v1), pk2(v2, v3)};
;             st_wt(ea.outb + (size_t)row * N + c0, o);
;           }
;         }
	v_mul_f32_e32 v188, v64, v168
	v_mul_f32_e32 v189, v68, v168
	v_mul_f32_e32 v190, v72, v168
	v_mul_f32_e32 v191, v76, v168
	v_max_f32_e32 v188, 0, v188
	v_max_f32_e32 v189, 0, v189
	v_max_f32_e32 v190, 0, v190
	v_max_f32_e32 v191, 0, v191
	v_pk_mul_f32 v[188:189], v[188:189], v[188:189]
	v_pk_mul_f32 v[190:191], v[190:191], v[190:191]
	v_cvt_pk_bf16_f32 v204, v188, v189
	v_cvt_pk_bf16_f32 v205, v190, v191
	v_add_u32_e32 v214, 0xc0000, v212
	global_store_dwordx2 v214, v[204:205], s[46:47] sc1
	v_mul_f32_e32 v192, v65, v169
	v_mul_f32_e32 v193, v69, v169
	v_mul_f32_e32 v194, v73, v169
	v_mul_f32_e32 v195, v77, v169
	v_max_f32_e32 v192, 0, v192
	v_max_f32_e32 v193, 0, v193
	v_max_f32_e32 v194, 0, v194
	v_max_f32_e32 v195, 0, v195
	v_pk_mul_f32 v[192:193], v[192:193], v[192:193]
	v_pk_mul_f32 v[194:195], v[194:195], v[194:195]
	v_cvt_pk_bf16_f32 v206, v192, v193
	v_cvt_pk_bf16_f32 v207, v194, v195
	v_add_u32_e32 v213, 0xc4000, v212
	global_store_dwordx2 v213, v[206:207], s[46:47] sc1
	v_mul_f32_e32 v196, v66, v170
	v_mul_f32_e32 v197, v70, v170
	v_mul_f32_e32 v198, v74, v170
	v_mul_f32_e32 v199, v78, v170
	v_max_f32_e32 v196, 0, v196
	v_max_f32_e32 v197, 0, v197
	v_max_f32_e32 v198, 0, v198
	v_max_f32_e32 v199, 0, v199
	v_pk_mul_f32 v[196:197], v[196:197], v[196:197]
	v_pk_mul_f32 v[198:199], v[198:199], v[198:199]
	v_cvt_pk_bf16_f32 v208, v196, v197
	v_cvt_pk_bf16_f32 v209, v198, v199
	v_add_u32_e32 v214, 0xc8000, v212
	global_store_dwordx2 v214, v[208:209], s[46:47] sc1
	v_mul_f32_e32 v200, v67, v171
	v_mul_f32_e32 v201, v71, v171
	v_mul_f32_e32 v202, v75, v171
	v_mul_f32_e32 v203, v79, v171
	v_max_f32_e32 v200, 0, v200
	v_max_f32_e32 v201, 0, v201
	v_max_f32_e32 v202, 0, v202
	v_max_f32_e32 v203, 0, v203
	v_pk_mul_f32 v[200:201], v[200:201], v[200:201]
	v_pk_mul_f32 v[202:203], v[202:203], v[202:203]
	v_cvt_pk_bf16_f32 v210, v200, v201
	v_cvt_pk_bf16_f32 v211, v202, v203
	v_add_u32_e32 v213, 0xcc000, v212
	global_store_dwordx2 v213, v[210:211], s[46:47] sc1
	s_waitcnt lgkmcnt(3)
	v_mul_f32_e32 v188, v48, v172
	v_mul_f32_e32 v189, v52, v172
	v_mul_f32_e32 v190, v56, v172
	v_mul_f32_e32 v191, v60, v172
	v_max_f32_e32 v188, 0, v188
	v_max_f32_e32 v189, 0, v189
	v_max_f32_e32 v190, 0, v190
	v_max_f32_e32 v191, 0, v191
	v_pk_mul_f32 v[188:189], v[188:189], v[188:189]
	v_pk_mul_f32 v[190:191], v[190:191], v[190:191]
	v_cvt_pk_bf16_f32 v204, v188, v189
	v_cvt_pk_bf16_f32 v205, v190, v191
	v_add_u32_e32 v214, 0x200000, v212
	global_store_dwordx2 v214, v[204:205], s[46:47] sc1
	v_mul_f32_e32 v192, v49, v173
	v_mul_f32_e32 v193, v53, v173
	v_mul_f32_e32 v194, v57, v173
	v_mul_f32_e32 v195, v61, v173
	v_max_f32_e32 v192, 0, v192
	v_max_f32_e32 v193, 0, v193
	v_max_f32_e32 v194, 0, v194
	v_max_f32_e32 v195, 0, v195
	v_pk_mul_f32 v[192:193], v[192:193], v[192:193]
	v_pk_mul_f32 v[194:195], v[194:195], v[194:195]
	v_cvt_pk_bf16_f32 v206, v192, v193
	v_cvt_pk_bf16_f32 v207, v194, v195
	v_add_u32_e32 v213, 0x204000, v212
	global_store_dwordx2 v213, v[206:207], s[46:47] sc1
	v_mul_f32_e32 v196, v50, v174
	v_mul_f32_e32 v197, v54, v174
	v_mul_f32_e32 v198, v58, v174
	v_mul_f32_e32 v199, v62, v174
	v_max_f32_e32 v196, 0, v196
	v_max_f32_e32 v197, 0, v197
	v_max_f32_e32 v198, 0, v198
	v_max_f32_e32 v199, 0, v199
	v_pk_mul_f32 v[196:197], v[196:197], v[196:197]
	v_pk_mul_f32 v[198:199], v[198:199], v[198:199]
	v_cvt_pk_bf16_f32 v208, v196, v197
	v_cvt_pk_bf16_f32 v209, v198, v199
	v_add_u32_e32 v214, 0x208000, v212
	global_store_dwordx2 v214, v[208:209], s[46:47] sc1
	v_mul_f32_e32 v200, v51, v175
	v_mul_f32_e32 v201, v55, v175
	v_mul_f32_e32 v202, v59, v175
	v_mul_f32_e32 v203, v63, v175
	v_max_f32_e32 v200, 0, v200
	v_max_f32_e32 v201, 0, v201
	v_max_f32_e32 v202, 0, v202
	v_max_f32_e32 v203, 0, v203
	v_pk_mul_f32 v[200:201], v[200:201], v[200:201]
	v_pk_mul_f32 v[202:203], v[202:203], v[202:203]
	v_cvt_pk_bf16_f32 v210, v200, v201
	v_cvt_pk_bf16_f32 v211, v202, v203
	v_add_u32_e32 v213, 0x20c000, v212
	global_store_dwordx2 v213, v[210:211], s[46:47] sc1
	s_waitcnt lgkmcnt(2)
	v_mul_f32_e32 v188, v32, v176
	v_mul_f32_e32 v189, v36, v176
	v_mul_f32_e32 v190, v40, v176
	v_mul_f32_e32 v191, v44, v176
	v_max_f32_e32 v188, 0, v188
	v_max_f32_e32 v189, 0, v189
	v_max_f32_e32 v190, 0, v190
	v_max_f32_e32 v191, 0, v191
	v_pk_mul_f32 v[188:189], v[188:189], v[188:189]
	v_pk_mul_f32 v[190:191], v[190:191], v[190:191]
	v_cvt_pk_bf16_f32 v204, v188, v189
	v_cvt_pk_bf16_f32 v205, v190, v191
	v_add_u32_e32 v214, 0x240000, v212
	global_store_dwordx2 v214, v[204:205], s[46:47] sc1
	v_mul_f32_e32 v192, v33, v177
	v_mul_f32_e32 v193, v37, v177
	v_mul_f32_e32 v194, v41, v177
	v_mul_f32_e32 v195, v45, v177
	v_max_f32_e32 v192, 0, v192
	v_max_f32_e32 v193, 0, v193
	v_max_f32_e32 v194, 0, v194
	v_max_f32_e32 v195, 0, v195
	v_pk_mul_f32 v[192:193], v[192:193], v[192:193]
	v_pk_mul_f32 v[194:195], v[194:195], v[194:195]
	v_cvt_pk_bf16_f32 v206, v192, v193
	v_cvt_pk_bf16_f32 v207, v194, v195
	v_add_u32_e32 v213, 0x244000, v212
	global_store_dwordx2 v213, v[206:207], s[46:47] sc1
	v_mul_f32_e32 v196, v34, v178
	v_mul_f32_e32 v197, v38, v178
	v_mul_f32_e32 v198, v42, v178
	v_mul_f32_e32 v199, v46, v178
	v_max_f32_e32 v196, 0, v196
	v_max_f32_e32 v197, 0, v197
	v_max_f32_e32 v198, 0, v198
	v_max_f32_e32 v199, 0, v199
	v_pk_mul_f32 v[196:197], v[196:197], v[196:197]
	v_pk_mul_f32 v[198:199], v[198:199], v[198:199]
	v_cvt_pk_bf16_f32 v208, v196, v197
	v_cvt_pk_bf16_f32 v209, v198, v199
	v_add_u32_e32 v214, 0x248000, v212
	global_store_dwordx2 v214, v[208:209], s[46:47] sc1
	v_mul_f32_e32 v200, v35, v179
	v_mul_f32_e32 v201, v39, v179
	v_mul_f32_e32 v202, v43, v179
	v_mul_f32_e32 v203, v47, v179
	v_max_f32_e32 v200, 0, v200
	v_max_f32_e32 v201, 0, v201
	v_max_f32_e32 v202, 0, v202
	v_max_f32_e32 v203, 0, v203
	v_pk_mul_f32 v[200:201], v[200:201], v[200:201]
	v_pk_mul_f32 v[202:203], v[202:203], v[202:203]
	v_cvt_pk_bf16_f32 v210, v200, v201
	v_cvt_pk_bf16_f32 v211, v202, v203
	v_add_u32_e32 v213, 0x24c000, v212
	global_store_dwordx2 v213, v[210:211], s[46:47] sc1
	s_waitcnt lgkmcnt(1)
; template <int EPI, int N, int K>
; __device__ __forceinline__ void gemm_phase(const bf16_t* __restrict__ A, const bf16_t* __restrict__ Bt, const EpiArgs ea) {
;     ...
; #pragma unroll
;       for (int ai = 0; ai < 2; ++ai)
; #pragma unroll
;         for (int m = 0; m < 4; ++m) {
;           const f32x4 r4 = *(const f32x4*)(rstd_l + ai * 128 + wr * 64 + m * 16 + fq * 4);
; #pragma unroll
;           for (int j = 0; j < 4; ++j) {
;             const int row = brow + ai * 128 + wr * 64 + m * 16 + fq * 4 + j;
;             const float rs = r4[j];
;             float v0 = acc[ai][0][m][0][j] * rs, v1 = acc[ai][0][m][1][j] * rs, v2 = acc[ai][1][m][0][j] * rs, v3 = acc[ai][1][m][1][j] * rs;
;             if (EPI == EPI_MLP) {
;               v0 = fmaxf(v0, 0.f); v1 = fmaxf(v1, 0.f); v2 = fmaxf(v2, 0.f); v3 = fmaxf(v3, 0.f);
;               v0 *= v0; v1 *= v1; v2 *= v2; v3 *= v3;
;             }
;             u32x2 o = {pk2(v0, v1), pk2(v2, v3)};
;             st_wt(ea.outb + (size_t)row * N + c0, o);
;           }
;         }
	v_mul_f32_e32 v188, v16, v180
	v_mul_f32_e32 v189, v20, v180
	v_mul_f32_e32 v190, v24, v180
	v_mul_f32_e32 v191, v28, v180
	v_max_f32_e32 v188, 0, v188
	v_max_f32_e32 v189, 0, v189
	v_max_f32_e32 v190, 0, v190
	v_max_f32_e32 v191, 0, v191
	v_pk_mul_f32 v[188:189], v[188:189], v[188:189]
	v_pk_mul_f32 v[190:191], v[190:191], v[190:191]
	v_cvt_pk_bf16_f32 v204, v188, v189
	v_cvt_pk_bf16_f32 v205, v190, v191
	v_add_u32_e32 v214, 0x280000, v212
	global_store_dwordx2 v214, v[204:205], s[46:47] sc1
	v_mul_f32_e32 v192, v17, v181
	v_mul_f32_e32 v193, v21, v181
	v_mul_f32_e32 v194, v25, v181
	v_mul_f32_e32 v195, v29, v181
	v_max_f32_e32 v192, 0, v192
	v_max_f32_e32 v193, 0, v193
	v_max_f32_e32 v194, 0, v194
	v_max_f32_e32 v195, 0, v195
	v_pk_mul_f32 v[192:193], v[192:193], v[192:193]
	v_pk_mul_f32 v[194:195], v[194:195], v[194:195]
	v_cvt_pk_bf16_f32 v206, v192, v193
	v_cvt_pk_bf16_f32 v207, v194, v195
	v_add_u32_e32 v213, 0x284000, v212
	global_store_dwordx2 v213, v[206:207], s[46:47] sc1
	v_mul_f32_e32 v196, v18, v182
	v_mul_f32_e32 v197, v22, v182
	v_mul_f32_e32 v198, v26, v182
	v_mul_f32_e32 v199, v30, v182
	v_max_f32_e32 v196, 0, v196
	v_max_f32_e32 v197, 0, v197
	v_max_f32_e32 v198, 0, v198
	v_max_f32_e32 v199, 0, v199
	v_pk_mul_f32 v[196:197], v[196:197], v[196:197]
	v_pk_mul_f32 v[198:199], v[198:199], v[198:199]
	v_cvt_pk_bf16_f32 v208, v196, v197
	v_cvt_pk_bf16_f32 v209, v198, v199
	v_add_u32_e32 v214, 0x288000, v212
	global_store_dwordx2 v214, v[208:209], s[46:47] sc1
	v_mul_f32_e32 v200, v19, v183
	v_mul_f32_e32 v201, v23, v183
	v_mul_f32_e32 v202, v27, v183
	v_mul_f32_e32 v203, v31, v183
	v_max_f32_e32 v200, 0, v200
	v_max_f32_e32 v201, 0, v201
	v_max_f32_e32 v202, 0, v202
	v_max_f32_e32 v203, 0, v203
	v_pk_mul_f32 v[200:201], v[200:201], v[200:201]
	v_pk_mul_f32 v[202:203], v[202:203], v[202:203]
	v_cvt_pk_bf16_f32 v210, v200, v201
	v_cvt_pk_bf16_f32 v211, v202, v203
	v_add_u32_e32 v213, 0x28c000, v212
	global_store_dwordx2 v213, v[210:211], s[46:47] sc1
	s_waitcnt lgkmcnt(0)
	v_mul_f32_e32 v188, v0, v184
	v_mul_f32_e32 v189, v4, v184
	v_mul_f32_e32 v190, v8, v184
	v_mul_f32_e32 v191, v12, v184
	v_max_f32_e32 v188, 0, v188
	v_max_f32_e32 v189, 0, v189
	v_max_f32_e32 v190, 0, v190
	v_max_f32_e32 v191, 0, v191
	v_pk_mul_f32 v[188:189], v[188:189], v[188:189]
	v_pk_mul_f32 v[190:191], v[190:191], v[190:191]
	v_cvt_pk_bf16_f32 v204, v188, v189
	v_cvt_pk_bf16_f32 v205, v190, v191
	v_add_u32_e32 v214, 0x2c0000, v212
	global_store_dwordx2 v214, v[204:205], s[46:47] sc1
	v_mul_f32_e32 v192, v1, v185
	v_mul_f32_e32 v193, v5, v185
	v_mul_f32_e32 v194, v9, v185
	v_mul_f32_e32 v195, v13, v185
	v_max_f32_e32 v192, 0, v192
	v_max_f32_e32 v193, 0, v193
	v_max_f32_e32 v194, 0, v194
	v_max_f32_e32 v195, 0, v195
	v_pk_mul_f32 v[192:193], v[192:193], v[192:193]
	v_pk_mul_f32 v[194:195], v[194:195], v[194:195]
	v_cvt_pk_bf16_f32 v206, v192, v193
	v_cvt_pk_bf16_f32 v207, v194, v195
	v_add_u32_e32 v213, 0x2c4000, v212
	global_store_dwordx2 v213, v[206:207], s[46:47] sc1
	v_mul_f32_e32 v196, v2, v186
	v_mul_f32_e32 v197, v6, v186
	v_mul_f32_e32 v198, v10, v186
	v_mul_f32_e32 v199, v14, v186
	v_max_f32_e32 v196, 0, v196
	v_max_f32_e32 v197, 0, v197
	v_max_f32_e32 v198, 0, v198
	v_max_f32_e32 v199, 0, v199
	v_pk_mul_f32 v[196:197], v[196:197], v[196:197]
	v_pk_mul_f32 v[198:199], v[198:199], v[198:199]
	v_cvt_pk_bf16_f32 v208, v196, v197
	v_cvt_pk_bf16_f32 v209, v198, v199
	v_add_u32_e32 v214, 0x2c8000, v212
	global_store_dwordx2 v214, v[208:209], s[46:47] sc1
	v_mul_f32_e32 v200, v3, v187
	v_mul_f32_e32 v201, v7, v187
	v_mul_f32_e32 v202, v11, v187
	v_mul_f32_e32 v203, v15, v187
	v_max_f32_e32 v200, 0, v200
	v_max_f32_e32 v201, 0, v201
	v_max_f32_e32 v202, 0, v202
	v_max_f32_e32 v203, 0, v203
	v_pk_mul_f32 v[200:201], v[200:201], v[200:201]
	v_pk_mul_f32 v[202:203], v[202:203], v[202:203]
	v_cvt_pk_bf16_f32 v210, v200, v201
	v_cvt_pk_bf16_f32 v211, v202, v203
	v_add_u32_e32 v213, 0x2cc000, v212
	global_store_dwordx2 v213, v[210:211], s[46:47] sc1
	s_andn2_b64 vcc, exec, s[12:13]
	s_cbranch_vccz .LBB0_520
